# v8 + half of the workgroups enter the q up-projection GEMM phase ~6 us later (store bursts of one half overlap the MFMA loops of the other)
# speedup vs baseline: 1.0498x; 1.0038x over previous
.LBB0_811:
	s_or_b64 exec, exec, s[0:1]
	v_mov_b32_e32 v8, v254
	s_waitcnt lgkmcnt(0)
	s_barrier
	s_bitcmp0_b32 s2, 3
	s_cbranch_scc1 .Lstg8_go
	s_sleep 64
	s_sleep 64
	s_sleep 64
.Lstg8_go:
	s_cmpk_gt_i32 s2, 0x5ff
	v_readfirstlane_b32 s17, v8
	s_cbranch_scc1 .LBB0_825
	v_lshlrev_b32_e32 v0, 4, v8
	v_add_u32_e32 v1, 0x2000, v0
	v_ashrrev_i32_e32 v2, 31, v1
	v_lshrrev_b32_e32 v2, 22, v2
	v_add_u32_e32 v2, v1, v2
	v_ashrrev_i32_e32 v2, 10, v2
	v_mul_i32_i24_e32 v3, 0x400, v2
	v_sub_u32_e32 v1, v1, v3
	v_lshrrev_b32_e32 v3, 4, v1
	v_bitop3_b32 v1, v3, v1, 32 bitop3:0x6c
	v_ashrrev_i32_e32 v3, 31, v1
	v_lshrrev_b32_e32 v3, 26, v3
	v_add_u32_e32 v3, v1, v3
	v_lshlrev_b32_e32 v5, 3, v2
	v_ashrrev_i32_e32 v4, 6, v3
	v_and_b32_e32 v5, -16, v5
	v_and_b32_e32 v3, 0xc0, v3
	v_add_u32_e32 v5, v4, v5
	v_sub_u32_e32 v1, v1, v3
	v_mov_b32_e32 v3, 1
	v_and_b32_e32 v4, 3, v4
	s_mov_b32 s0, 0x7fffe0
	v_lshrrev_b32_e32 v6, 2, v5
	v_lshlrev_b32_e32 v7, 1, v5
	v_lshlrev_b32_e32 v2, 5, v2
	v_ashrrev_i16_sdwa v1, v3, sext(v1) dst_sel:DWORD dst_unused:UNUSED_PAD src0_sel:DWORD src1_sel:BYTE_0
	v_and_or_b32 v4, v5, s0, v4
	v_and_b32_e32 v6, 4, v6
	v_and_b32_e32 v7, 24, v7
	v_and_b32_e32 v2, 32, v2
	v_bfe_i32 v1, v1, 0, 16
	v_or3_b32 v4, v4, v6, v7
	v_add_lshl_u32 v1, v2, v1, 1
	v_lshl_add_u32 v160, v4, 9, v1
	v_lshl_add_u32 v162, v5, 9, v1
	v_bfe_i32 v1, v8, 27, 1
	v_lshrrev_b32_e32 v1, 22, v1
	v_add_u32_e32 v1, v0, v1
	v_and_b32_e32 v1, 0xfffffc00, v1
	v_sub_u32_e32 v0, v0, v1
	v_ashrrev_i32_e32 v2, 31, v8
	v_lshrrev_b32_e32 v1, 4, v0
	v_lshrrev_b32_e32 v2, 26, v2
	v_bitop3_b32 v1, v1, v0, 32 bitop3:0x6c
	v_ashrrev_i32_e32 v0, 31, v0
	v_add_u32_e32 v2, v8, v2
	v_lshrrev_b32_e32 v0, 26, v0
	v_ashrrev_i32_e32 v2, 6, v2
	v_add_u32_e32 v0, v1, v0
	v_lshlrev_b32_e32 v4, 3, v2
	s_add_u32 s72, s28, 0x17c00000
	v_ashrrev_i32_e32 v0, 6, v0
	v_and_b32_e32 v4, -16, v4
	s_addc_u32 s73, s29, 0
	v_add_u32_e32 v4, v0, v4
	v_and_b32_e32 v5, 3, v0
	s_ashr_i32 s3, s2, 31
	v_and_or_b32 v5, v4, s0, v5
	s_lshr_b32 s0, s3, 29
	s_add_i32 s0, s2, s0
	s_ashr_i32 s1, s17, 6
	s_ashr_i32 s7, s0, 3
	s_and_b32 s0, s0, -8
	s_ashr_i32 s6, s17, 8
	s_lshl_b32 s74, s1, 10
	s_sub_i32 s0, s2, s0
	s_cmp_lt_i32 s0, 0
	s_movk_i32 s75, 0xc1
	s_cselect_b32 s8, s75, 0xc0
	s_mul_i32 s0, s8, s0
	s_add_i32 s0, s0, s7
	s_mul_hi_i32 s7, s0, 0x2aaaaaab
	s_lshr_b32 s8, s7, 31
	s_ashr_i32 s7, s7, 4
	s_add_i32 s7, s7, s8
	s_lshl_b32 s8, s7, 3
	s_mulk_i32 s7, 0x60
	s_sub_i32 s7, s0, s7
	s_bfe_i32 s0, s7, 0x80000
	s_bfe_u32 s0, s0, 0x3000c
	s_add_i32 s9, s7, s0
	s_bfe_i32 s0, s9, 0x80000
	s_and_b32 s9, s9, 0xf8
	s_sub_i32 s7, s7, s9
	s_sext_i32_i16 s0, s0
	s_sext_i32_i8 s7, s7
	v_mul_i32_i24_e32 v0, 64, v0
	s_lshr_b32 s0, s0, 3
	s_add_i32 s62, s8, s7
	v_sub_u32_e32 v0, v1, v0
	s_ashr_i32 s63, s62, 31
	s_bfe_i64 s[12:13], s[0:1], 0x100000
	v_lshrrev_b32_e32 v6, 2, v4
	v_lshlrev_b32_e32 v7, 1, v4
	v_lshlrev_b32_e32 v2, 5, v2
	v_ashrrev_i16_sdwa v0, v3, sext(v0) dst_sel:DWORD dst_unused:UNUSED_PAD src0_sel:DWORD src1_sel:BYTE_0
	s_lshl_b64 s[8:9], s[62:63], 17
	s_lshl_b64 s[12:13], s[12:13], 17
	v_and_b32_e32 v6, 4, v6
	v_and_b32_e32 v7, 24, v7
	v_and_b32_e32 v2, 32, v2
	v_bfe_i32 v0, v0, 0, 16
	s_add_u32 s66, s68, s12
	v_or3_b32 v5, v5, v6, v7
	v_add_lshl_u32 v0, v2, v0, 1
	s_addc_u32 s67, s69, s13
	s_add_i32 s63, s74, 0
	v_lshl_add_u32 v164, v5, 9, v0
	s_add_i32 m0, s63, 0x10000
	v_lshl_add_u32 v166, v4, 9, v0
	global_load_lds_dwordx4 v164, s[66:67]
	s_add_i32 m0, s63, 0x12000
	s_add_u32 s64, s72, s8
	global_load_lds_dwordx4 v160, s[66:67]
	s_addc_u32 s65, s73, s9
	s_mov_b32 m0, s63
	s_add_i32 s76, s63, 0x2000
	global_load_lds_dwordx4 v166, s[64:65]
	s_mov_b32 m0, s76
	s_add_u32 s8, s66, 0x10000
	global_load_lds_dwordx4 v162, s[64:65]
	s_addc_u32 s9, s67, 0
	s_add_i32 m0, s63, 0x14000
	v_mov_b32_e32 v169, 0
	global_load_lds_dwordx4 v164, s[8:9]
	s_add_i32 m0, s63, 0x16000
	v_mov_b32_e32 v165, v169
	global_load_lds_dwordx4 v160, s[8:9]
	s_add_u32 s8, s64, 0x10000
	s_addc_u32 s9, s65, 0
	s_add_i32 s77, s63, 0x4000
	s_mov_b32 m0, s77
	s_add_i32 s78, s63, 0x6000
	global_load_lds_dwordx4 v166, s[8:9]
	s_mov_b32 m0, s78
	v_mov_b32_e32 v161, v169
	global_load_lds_dwordx4 v162, s[8:9]
	v_mov_b32_e32 v167, v169
	v_mov_b32_e32 v163, v169
	s_movk_i32 s79, 0x2000
	s_movk_i32 s80, 0xf8
	v_lshl_add_u64 v[6:7], s[66:67], 0, v[164:165]
	v_lshl_add_u64 v[4:5], s[66:67], 0, v[160:161]
	v_lshl_add_u64 v[2:3], s[64:65], 0, v[166:167]
	s_cmp_lg_u32 s6, 1
	v_lshl_add_u64 v[0:1], s[64:65], 0, v[162:163]
	s_cbranch_scc1 .LBB0_814
	s_barrier
